# P3 dequeue: ds ops instead of flat, double-buffered slot (one barrier per item)
# speedup vs baseline: 1.0064x; 1.0064x over previous
.LBB0_325:
	s_and_saveexec_b64 s[10:11], s[38:39]
	s_cbranch_execz .LBB0_329
	s_bitcmp1_b32 s32, 0
	s_cbranch_scc0 .Lq_fresh
	s_waitcnt vmcnt(0)
	v_mov_b32_e32 v0, v164
	s_branch .Lq_join
.Lq_fresh:
	v_mov_b32_e32 v2, 1
	global_atomic_add v0, v1, v2, s[24:25] sc0
	s_waitcnt vmcnt(0)
.Lq_join:
	s_lshl_b32 s14, s32, 1
	s_and_b32 s14, s14, 4
	s_add_i32 s14, s14, 0x20040
	v_mov_b32_e32 v2, s14
	ds_write_b32 v2, v0
.LBB0_329:
	s_or_b64 exec, exec, s[10:11]
	s_lshl_b32 s14, s32, 1
	s_and_b32 s14, s14, 4
	s_add_i32 s14, s14, 0x20040
	v_mov_b32_e32 v2, s14
	s_and_b32 s32, s32, 2
	s_xor_b32 s32, s32, 2
	s_waitcnt lgkmcnt(0)
	s_barrier
	ds_read_b32 v0, v2
	s_mov_b64 s[10:11], -1
	s_waitcnt lgkmcnt(0)
	v_readfirstlane_b32 s42, v0
	s_cmpk_gt_i32 s42, 0x747
	s_cbranch_scc1 .LBB0_324
	s_cmpk_gt_i32 s42, 0x47
	s_cbranch_scc0 .LBB0_405
	s_cmpk_gt_u32 s42, 0x2c7
	s_cbranch_scc0 .LBB0_346
	s_mov_b64 s[10:11], exec
	s_and_b64 exec, exec, s[38:39]
	s_cbranch_execz .Lq_noissue
	v_mov_b32_e32 v165, 1
	global_atomic_add v164, v1, v165, s[24:25] sc0
.Lq_noissue:
	s_mov_b64 exec, s[10:11]
	s_or_b32 s32, s32, 1
	s_add_i32 s14, s42, 0xfbb8
	s_add_i32 s10, s42, 0xfffffd38
	s_add_i32 s11, s42, 0xfffffbb8
	s_and_b32 s14, s14, 0xffff
	s_cmpk_lt_u32 s14, 0x180
	s_cselect_b32 s14, 2, 4
	s_cmpk_lt_u32 s10, 0x180
	s_cselect_b32 s47, 0, s14
	s_cmpk_lt_u32 s11, 0x180
	s_cselect_b32 s11, 3, 1
	s_cselect_b32 s14, 7, 1
	s_cmpk_lt_u32 s10, 0x180
	s_cselect_b32 s11, 5, s11
	s_cselect_b32 s14, 31, s14
	s_and_b32 s26, s10, 0xffff
	s_mul_i32 s26, s26, 0xaaab
	s_lshr_b32 s27, s26, 24
	s_mul_i32 s26, s27, 0x180
	s_sub_i32 s10, s10, s26
	s_and_b32 s43, s10, 0xffff
	s_and_b32 s43, s14, s43
	s_bfe_u32 s26, s10, 0xb0005
	s_and_b32 s10, s10, 31
	s_lshl_b32 s49, s43, 8
	s_lshr_b32 s48, s10, s11
	v_add_u32_e32 v0, s49, v205
	s_lshl_b32 s14, s26, 7
	s_movk_i32 s10, 0x7f
	v_lshl_add_u64 v[50:51], v[180:181], 0, s[14:15]
	v_cmp_lt_i32_e32 vcc, s10, v0
	v_mov_b32_e32 v2, 0
	v_mov_b32_e32 v6, 0
	v_mov_b32_e32 v7, 0
	v_mov_b32_e32 v8, 0
	v_mov_b32_e32 v9, 0
	v_mov_b32_e32 v10, 0
	v_mov_b32_e32 v11, 0
	v_mov_b32_e32 v12, 0
	v_mov_b32_e32 v13, 0
	s_and_saveexec_b64 s[10:11], vcc
	s_cbranch_execz .LBB0_334
	v_add_u32_e32 v3, 0xffffff80, v0
	v_lshlrev_b32_e32 v3, s47, v3
	v_add_u32_e32 v3, s48, v3
	v_mad_u64_u32 v[4:5], s[50:51], v3, s35, v[50:51]
	global_load_dwordx4 v[6:9], v[4:5], off offset:1536
	global_load_dwordx4 v[10:13], v[4:5], off offset:3072
